# P3 prompt attention steps: the 16 transposed V fragment LDS reads issued right after the QK MFMAs into spare VGPRs (their latency runs under mask + softmax) instead of in front of the PV MFMAs
# speedup vs baseline: 1.0121x; 1.0046x over previous
.LBB0_1675:
	v_max3_f32 v70, v0, s80, v1
	v_max3_f32 v70, v70, v2, v3
	v_max3_f32 v70, v70, v4, v5
	v_max3_f32 v70, v70, v6, v7
	v_max3_f32 v70, v70, v8, v9
	v_max3_f32 v70, v70, v10, v11
	v_cmp_lt_i32_e32 vcc, v87, v88
	v_max3_f32 v70, v70, v12, v13
	v_max3_f32 v70, v70, v14, v15
	v_cndmask_b32_e32 v71, v133, v87, vcc
	v_lshlrev_b32_e32 v71, 2, v71
	ds_bpermute_b32 v71, v71, v70
	v_cmp_lt_i32_e32 vcc, v89, v88
	s_waitcnt lgkmcnt(0)
	v_max_f32_e32 v71, v71, v71
	v_max_f32_e32 v70, v70, v71
	v_cndmask_b32_e32 v71, v133, v89, vcc
	v_lshlrev_b32_e32 v71, 2, v71
	ds_bpermute_b32 v71, v71, v70
	s_waitcnt lgkmcnt(0)
	v_max3_f32 v71, v92, v70, v71
	v_cmp_neq_f32_e32 vcc, s80, v71
	s_nop 1
	v_cndmask_b32_e32 v100, 0, v71, vcc
	v_sub_f32_e32 v0, v0, v100
	v_sub_f32_e32 v1, v1, v100
	v_sub_f32_e32 v70, v92, v100
	v_exp_f32_e32 v92, v0
	v_exp_f32_e32 v93, v1
	v_sub_f32_e32 v0, v2, v100
	v_exp_f32_e32 v94, v0
	v_sub_f32_e32 v0, v3, v100
	v_exp_f32_e32 v95, v0
	v_sub_f32_e32 v1, v4, v100
	v_add_f32_e32 v0, 0, v92
	v_exp_f32_e32 v96, v1
	v_sub_f32_e32 v1, v5, v100
	v_add_f32_e32 v0, v93, v0
	v_exp_f32_e32 v97, v1
	v_sub_f32_e32 v1, v6, v100
	v_add_f32_e32 v0, v94, v0
	v_exp_f32_e32 v98, v1
	v_sub_f32_e32 v1, v7, v100
	v_add_f32_e32 v0, v95, v0
	v_exp_f32_e32 v7, v1
	v_add_f32_e32 v0, v96, v0
	v_add_f32_e32 v0, v97, v0
	v_add_f32_e32 v0, v98, v0
	v_add_f32_e32 v101, v7, v0
	v_sub_f32_e32 v0, v8, v100
	v_exp_f32_e32 v102, v0
	v_sub_f32_e32 v0, v9, v100
	v_exp_f32_e32 v103, v0
	v_sub_f32_e32 v0, v10, v100
	v_exp_f32_e32 v70, v70
	v_exp_f32_e32 v104, v0
	v_sub_f32_e32 v0, v11, v100
	v_exp_f32_e32 v105, v0
	v_sub_f32_e32 v0, v12, v100
	v_exp_f32_e32 v106, v0
	v_sub_f32_e32 v0, v13, v100
	v_exp_f32_e32 v107, v0
	v_pk_mul_f32 v[2:3], v[54:55], v[70:71] op_sel_hi:[1,0]
	v_pk_mul_f32 v[0:1], v[52:53], v[70:71] op_sel_hi:[1,0]
	v_cvt_pk_bf16_f32 v4, v92, v93
	v_cvt_pk_bf16_f32 v5, v94, v95
	v_cvt_pk_bf16_f32 v6, v96, v97
	v_cvt_pk_bf16_f32 v7, v98, v7
	s_waitcnt lgkmcnt(0)
	v_sub_f32_e32 v12, v14, v100
	s_nop 0
	v_mfma_f32_16x16x32_bf16 v[0:3], v[140:143], v[4:7], v[0:3]
	v_mul_f32_e64 v50, v50, v70
	v_mul_f32_e64 v51, v51, v70
	v_pk_mul_f32 v[48:49], v[48:49], v[70:71] op_sel_hi:[1,0]
	v_exp_f32_e32 v96, v12
	v_pk_mul_f32 v[12:13], v[44:45], v[70:71] op_sel_hi:[1,0]
	v_mfma_f32_16x16x32_bf16 v[48:51], v[144:147], v[4:7], v[48:51]
	v_sub_f32_e32 v92, v15, v100
	v_pk_mul_f32 v[14:15], v[46:47], v[70:71] op_sel_hi:[1,0]
	v_pk_mul_f32 v[26:27], v[26:27], v[70:71] op_sel_hi:[1,0]
	v_pk_mul_f32 v[24:25], v[24:25], v[70:71] op_sel_hi:[1,0]
	v_mfma_f32_16x16x32_bf16 v[12:15], v[148:151], v[4:7], v[12:15]
	v_exp_f32_e32 v97, v92
	v_mfma_f32_16x16x32_bf16 v[4:7], v[152:155], v[4:7], v[24:27]
	s_waitcnt lgkmcnt(0)
	v_cvt_pk_bf16_f32 v8, v102, v103
	v_cvt_pk_bf16_f32 v9, v104, v105
	v_cvt_pk_bf16_f32 v10, v106, v107
	v_cvt_pk_bf16_f32 v11, v96, v97
	s_nop 0
	v_mfma_f32_16x16x32_bf16 v[52:55], v[156:159], v[8:11], v[0:3]
	s_nop 2
	v_add_f32_e32 v0, v102, v101
	v_add_f32_e32 v0, v103, v0
	v_add_f32_e32 v0, v104, v0
	v_add_f32_e32 v0, v105, v0
	v_add_f32_e32 v0, v106, v0
	v_add_f32_e32 v0, v107, v0
	v_mfma_f32_16x16x32_bf16 v[48:51], v[160:163], v[8:11], v[48:51]
	v_add_f32_e32 v0, v96, v0
	v_add_f32_e32 v0, v97, v0
	v_fmac_f32_e32 v0, v83, v70
	v_mfma_f32_16x16x32_bf16 v[44:47], v[164:167], v[8:11], v[12:15]
	v_mov_b32_e32 v83, v0
	v_mov_b32_e32 v92, v71
	v_mfma_f32_16x16x32_bf16 v[24:27], v[168:171], v[8:11], v[4:7]

.LBB0_1682:
	s_add_i32 s0, s88, -3
	v_cmp_lt_u32_e32 vcc, s0, v73
	s_and_b64 s[0:1], s[10:11], vcc
	s_and_saveexec_b64 s[66:67], s[0:1]
	s_cbranch_execz .LBB0_1686
	ds_read_b128 v[0:3], v64
	ds_read_b128 v[4:7], v64 offset:64
	ds_read_b128 v[8:11], v64 offset:2560
	ds_read_b128 v[12:15], v64 offset:2624
	ds_read_b128 v[94:97], v64 offset:5120
	ds_read_b128 v[98:101], v64 offset:5184
	v_and_b32_e32 v93, v68, v59
	s_waitcnt lgkmcnt(5)
	v_mfma_f32_16x16x32_bf16 v[0:3], v[0:3], v[16:19], 0
	v_and_b32_e32 v106, v68, v75
	v_cmp_ne_u32_e32 vcc, 0, v93
	v_and_b32_e32 v93, v68, v76
	s_waitcnt lgkmcnt(3)
	v_mfma_f32_16x16x32_bf16 v[8:11], v[8:11], v[16:19], 0
	s_cmp_lt_u32 s90, s86
	v_mfma_f32_16x16x32_bf16 v[0:3], v[4:7], v[20:23], v[0:3]
	ds_read_b128 v[4:7], v64 offset:7680
	ds_read_b128 v[102:105], v64 offset:7744
	s_waitcnt lgkmcnt(4)
	v_mfma_f32_16x16x32_bf16 v[8:11], v[12:15], v[20:23], v[8:11]
	s_nop 3
	v_cndmask_b32_e32 v0, v86, v0, vcc
	v_cmp_ne_u32_e32 vcc, 0, v106
	s_waitcnt lgkmcnt(3)
	v_mfma_f32_16x16x32_bf16 v[12:15], v[94:97], v[16:19], 0
	v_cndmask_b32_e32 v1, v86, v1, vcc
	v_cmp_ne_u32_e32 vcc, 0, v93
	v_and_b32_e32 v93, v68, v77
	s_waitcnt lgkmcnt(1)
	v_mfma_f32_16x16x32_bf16 v[94:97], v[4:7], v[16:19], 0
	v_cndmask_b32_e32 v2, v86, v2, vcc
	v_cmp_ne_u32_e32 vcc, 0, v93
	v_and_b32_e32 v4, v68, v78
	v_and_b32_e32 v5, v68, v79
	v_cndmask_b32_e32 v3, v86, v3, vcc
	v_cmp_ne_u32_e32 vcc, 0, v4
	v_mfma_f32_16x16x32_bf16 v[12:15], v[98:101], v[20:23], v[12:15]
	v_and_b32_e32 v6, v68, v80
	v_cndmask_b32_e32 v4, v86, v8, vcc
	v_cmp_ne_u32_e32 vcc, 0, v5
	v_and_b32_e32 v7, v68, v81
	v_and_b32_e32 v8, v69, v59
	v_cndmask_b32_e32 v5, v86, v9, vcc
	v_cmp_ne_u32_e32 vcc, 0, v6
	v_and_b32_e32 v9, v69, v75
	s_waitcnt lgkmcnt(0)
	ds_read_b64_tr_b16 v[140:141], v74
	ds_read_b64_tr_b16 v[144:145], v74 offset:32
	ds_read_b64_tr_b16 v[148:149], v74 offset:64
	ds_read_b64_tr_b16 v[152:153], v74 offset:96
	ds_read_b64_tr_b16 v[142:143], v74 offset:2560
	ds_read_b64_tr_b16 v[146:147], v74 offset:2592
	ds_read_b64_tr_b16 v[150:151], v74 offset:2624
	ds_read_b64_tr_b16 v[154:155], v74 offset:2656
	ds_read_b64_tr_b16 v[156:157], v82
	ds_read_b64_tr_b16 v[160:161], v82 offset:32
	ds_read_b64_tr_b16 v[164:165], v82 offset:64
	ds_read_b64_tr_b16 v[168:169], v82 offset:96
	ds_read_b64_tr_b16 v[158:159], v82 offset:2560
	ds_read_b64_tr_b16 v[162:163], v82 offset:2592
	ds_read_b64_tr_b16 v[166:167], v82 offset:2624
	ds_read_b64_tr_b16 v[170:171], v82 offset:2656
	v_mfma_f32_16x16x32_bf16 v[94:97], v[102:105], v[20:23], v[94:97]
	v_cndmask_b32_e32 v6, v86, v10, vcc
	v_cmp_ne_u32_e32 vcc, 0, v7
	v_and_b32_e32 v10, v69, v76
	s_nop 0
	v_cndmask_b32_e32 v7, v86, v11, vcc
	v_cmp_ne_u32_e32 vcc, 0, v8
	v_and_b32_e32 v11, v69, v77
	s_nop 0
	v_cndmask_b32_e32 v8, v86, v12, vcc
	v_cmp_ne_u32_e32 vcc, 0, v9
	v_and_b32_e32 v12, v69, v78
	s_nop 0
	v_cndmask_b32_e32 v9, v86, v13, vcc
	v_cmp_ne_u32_e32 vcc, 0, v10
	v_and_b32_e32 v13, v69, v79
	s_nop 0
	v_cndmask_b32_e32 v10, v86, v14, vcc
	v_cmp_ne_u32_e32 vcc, 0, v11
	v_and_b32_e32 v14, v69, v80
	v_cmp_ne_u32_e64 s[0:1], 0, v14
	v_cndmask_b32_e32 v11, v86, v15, vcc
	v_cmp_ne_u32_e32 vcc, 0, v12
	v_and_b32_e32 v15, v69, v81
	v_cndmask_b32_e64 v14, v86, v96, s[0:1]
	v_cndmask_b32_e32 v12, v86, v94, vcc
	v_cmp_ne_u32_e32 vcc, 0, v13
	s_nop 1
	v_cndmask_b32_e32 v13, v86, v95, vcc
	v_cmp_ne_u32_e32 vcc, 0, v15
	s_nop 1
	v_cndmask_b32_e32 v15, v86, v97, vcc
	s_cbranch_scc1 .LBB0_1685
	v_add_u32_e32 v68, s90, v72
	v_cmp_gt_u32_e32 vcc, s86, v68
	v_add_u32_e32 v69, 1, v68
	s_nop 0
	v_cndmask_b32_e32 v0, v86, v0, vcc
	v_cmp_gt_u32_e32 vcc, s86, v69
	v_add_u32_e32 v69, 2, v68
	s_nop 0
	v_cndmask_b32_e32 v1, v86, v1, vcc
	v_cmp_gt_u32_e32 vcc, s86, v69
	v_add_u32_e32 v69, 3, v68
	s_nop 0
	v_cndmask_b32_e32 v2, v86, v2, vcc
	v_cmp_gt_u32_e32 vcc, s86, v69
	v_add_u32_e32 v69, 16, v68
	v_cmp_gt_u32_e64 s[0:1], s86, v69
	v_add_u32_e32 v69, 17, v68
	v_cmp_gt_u32_e64 s[2:3], s86, v69
	v_add_u32_e32 v69, 18, v68
	v_cmp_gt_u32_e64 s[4:5], s86, v69
	v_add_u32_e32 v69, 19, v68
	v_cmp_gt_u32_e64 s[6:7], s86, v69
	v_add_u32_e32 v69, 32, v68
	v_cmp_gt_u32_e64 s[12:13], s86, v69
	v_add_u32_e32 v69, 33, v68
	v_cmp_gt_u32_e64 s[14:15], s86, v69
	v_add_u32_e32 v69, 34, v68
	v_cmp_gt_u32_e64 s[16:17], s86, v69
	v_add_u32_e32 v69, 35, v68
	v_cmp_gt_u32_e64 s[18:19], s86, v69
	v_add_u32_e32 v69, 48, v68
	v_cmp_gt_u32_e64 s[20:21], s86, v69
	v_add_u32_e32 v69, 49, v68
	v_cmp_gt_u32_e64 s[22:23], s86, v69
	v_add_u32_e32 v69, 50, v68
	v_add_u32_e32 v68, 51, v68
	v_cmp_gt_u32_e64 s[24:25], s86, v69
	v_cmp_gt_u32_e64 s[26:27], s86, v68
	s_or_b64 s[24:25], s[26:27], s[24:25]
	s_or_b64 s[22:23], s[24:25], s[22:23]
	s_or_b64 s[20:21], s[22:23], s[20:21]
	s_or_b64 s[18:19], s[20:21], s[18:19]
	s_or_b64 s[16:17], s[18:19], s[16:17]
	s_or_b64 s[14:15], s[16:17], s[14:15]
	s_or_b64 s[12:13], s[14:15], s[12:13]
	s_or_b64 s[6:7], s[12:13], s[6:7]
	s_or_b64 s[4:5], s[6:7], s[4:5]
	s_or_b64 s[2:3], s[4:5], s[2:3]
	s_or_b64 s[0:1], s[2:3], s[0:1]
	s_or_b64 vcc, s[0:1], vcc
	v_cndmask_b32_e64 v14, v86, v14, s[24:25]
	v_cndmask_b32_e64 v13, v86, v13, s[22:23]
	v_cndmask_b32_e64 v12, v86, v12, s[20:21]
	v_cndmask_b32_e64 v11, v86, v11, s[18:19]
	v_cndmask_b32_e64 v10, v86, v10, s[16:17]
	v_cndmask_b32_e64 v9, v86, v9, s[14:15]
	v_cndmask_b32_e64 v8, v86, v8, s[12:13]
	v_cndmask_b32_e64 v7, v86, v7, s[6:7]
	v_cndmask_b32_e64 v6, v86, v6, s[4:5]
	v_cndmask_b32_e64 v5, v86, v5, s[2:3]
	v_cndmask_b32_e64 v4, v86, v4, s[0:1]
	v_cndmask_b32_e32 v3, v86, v3, vcc
	v_cndmask_b32_e64 v15, v86, v15, s[26:27]
.LBB0_1685:
	v_max3_f32 v68, v0, s80, v1
	v_max3_f32 v68, v68, v2, v3
	v_max3_f32 v68, v68, v4, v5
	v_max3_f32 v68, v68, v6, v7
	v_max3_f32 v68, v68, v8, v9
	v_max3_f32 v68, v68, v10, v11
	v_cmp_lt_i32_e32 vcc, v87, v88
	v_max3_f32 v68, v68, v12, v13
	v_max3_f32 v68, v68, v14, v15
	v_cndmask_b32_e32 v69, v133, v87, vcc
	v_lshlrev_b32_e32 v69, 2, v69
	ds_bpermute_b32 v69, v69, v68
	v_cmp_lt_i32_e32 vcc, v89, v88
	s_waitcnt lgkmcnt(0)
	v_max_f32_e32 v69, v69, v69
	v_max_f32_e32 v68, v68, v69
	v_cndmask_b32_e32 v69, v133, v89, vcc
	v_lshlrev_b32_e32 v69, 2, v69
	ds_bpermute_b32 v69, v69, v68
	s_waitcnt lgkmcnt(0)
	v_max3_f32 v69, v92, v68, v69
	v_cmp_neq_f32_e32 vcc, s80, v69
	s_nop 1
	v_cndmask_b32_e32 v100, 0, v69, vcc
	v_sub_f32_e32 v0, v0, v100
	v_sub_f32_e32 v1, v1, v100
	v_sub_f32_e32 v68, v92, v100
	v_exp_f32_e32 v92, v0
	v_exp_f32_e32 v93, v1
	v_sub_f32_e32 v0, v2, v100
	v_exp_f32_e32 v94, v0
	v_sub_f32_e32 v0, v3, v100
	v_exp_f32_e32 v95, v0
	v_sub_f32_e32 v1, v4, v100
	v_add_f32_e32 v0, 0, v92
	v_exp_f32_e32 v96, v1
	v_sub_f32_e32 v1, v5, v100
	v_add_f32_e32 v0, v93, v0
	v_exp_f32_e32 v97, v1
	v_sub_f32_e32 v1, v6, v100
	v_add_f32_e32 v0, v94, v0
	v_exp_f32_e32 v98, v1
	v_sub_f32_e32 v1, v7, v100
	v_add_f32_e32 v0, v95, v0
	v_exp_f32_e32 v7, v1
	v_add_f32_e32 v0, v96, v0
	v_add_f32_e32 v0, v97, v0
	v_add_f32_e32 v0, v98, v0
	v_add_f32_e32 v101, v7, v0
	v_sub_f32_e32 v0, v8, v100
	v_exp_f32_e32 v102, v0
	v_sub_f32_e32 v0, v9, v100
	v_exp_f32_e32 v103, v0
	v_sub_f32_e32 v0, v10, v100
	v_exp_f32_e32 v68, v68
	v_exp_f32_e32 v104, v0
	v_sub_f32_e32 v0, v11, v100
	v_exp_f32_e32 v105, v0
	v_sub_f32_e32 v0, v12, v100
	v_exp_f32_e32 v106, v0
	v_sub_f32_e32 v0, v13, v100
	v_exp_f32_e32 v107, v0
	v_pk_mul_f32 v[2:3], v[54:55], v[68:69] op_sel_hi:[1,0]
	v_pk_mul_f32 v[0:1], v[52:53], v[68:69] op_sel_hi:[1,0]
	v_cvt_pk_bf16_f32 v4, v92, v93
	v_cvt_pk_bf16_f32 v5, v94, v95
	v_cvt_pk_bf16_f32 v6, v96, v97
	v_cvt_pk_bf16_f32 v7, v98, v7
	s_waitcnt lgkmcnt(0)
	v_sub_f32_e32 v12, v14, v100
	s_nop 0
	v_mfma_f32_16x16x32_bf16 v[0:3], v[140:143], v[4:7], v[0:3]
	v_mul_f32_e64 v50, v50, v68
	v_mul_f32_e64 v51, v51, v68
	v_pk_mul_f32 v[48:49], v[48:49], v[68:69] op_sel_hi:[1,0]
	v_exp_f32_e32 v96, v12
	v_pk_mul_f32 v[12:13], v[44:45], v[68:69] op_sel_hi:[1,0]
	v_mfma_f32_16x16x32_bf16 v[48:51], v[144:147], v[4:7], v[48:51]
	v_sub_f32_e32 v92, v15, v100
	v_pk_mul_f32 v[14:15], v[46:47], v[68:69] op_sel_hi:[1,0]
	v_pk_mul_f32 v[26:27], v[26:27], v[68:69] op_sel_hi:[1,0]
	v_pk_mul_f32 v[24:25], v[24:25], v[68:69] op_sel_hi:[1,0]
	v_mfma_f32_16x16x32_bf16 v[12:15], v[148:151], v[4:7], v[12:15]
	v_exp_f32_e32 v97, v92
	v_mfma_f32_16x16x32_bf16 v[4:7], v[152:155], v[4:7], v[24:27]
	s_waitcnt lgkmcnt(0)
	v_cvt_pk_bf16_f32 v8, v102, v103
	v_cvt_pk_bf16_f32 v9, v104, v105
	v_cvt_pk_bf16_f32 v10, v106, v107
	v_cvt_pk_bf16_f32 v11, v96, v97
	s_nop 0
	v_mfma_f32_16x16x32_bf16 v[52:55], v[156:159], v[8:11], v[0:3]
	s_nop 2
	v_add_f32_e32 v0, v102, v101
	v_add_f32_e32 v0, v103, v0
	v_add_f32_e32 v0, v104, v0
	v_add_f32_e32 v0, v105, v0
	v_add_f32_e32 v0, v106, v0
	v_add_f32_e32 v0, v107, v0
	v_mfma_f32_16x16x32_bf16 v[48:51], v[160:163], v[8:11], v[48:51]
	v_add_f32_e32 v0, v96, v0
	v_add_f32_e32 v0, v97, v0
	v_fmac_f32_e32 v0, v83, v68
	v_mfma_f32_16x16x32_bf16 v[44:47], v[164:167], v[8:11], v[12:15]
	v_mov_b32_e32 v83, v0
	v_mov_b32_e32 v92, v69
	v_mfma_f32_16x16x32_bf16 v[24:27], v[168:171], v[8:11], v[4:7]

.LBB0_1693:
	ds_read_b128 v[0:3], v64 offset:32768
	ds_read_b128 v[4:7], v64 offset:32832
	ds_read_b128 v[8:11], v64 offset:35328
	ds_read_b128 v[12:15], v64 offset:35392
	ds_read_b128 v[94:97], v64 offset:37888
	ds_read_b128 v[98:101], v64 offset:37952
	v_and_b32_e32 v93, v70, v59
	s_waitcnt lgkmcnt(5)
	v_mfma_f32_16x16x32_bf16 v[0:3], v[0:3], v[16:19], 0
	v_and_b32_e32 v106, v70, v75
	v_cmp_ne_u32_e32 vcc, 0, v93
	v_and_b32_e32 v93, v70, v76
	s_waitcnt lgkmcnt(3)
	v_mfma_f32_16x16x32_bf16 v[8:11], v[8:11], v[16:19], 0
	s_add_i32 s0, s90, 64
	s_cmp_le_u32 s0, s89
	v_mfma_f32_16x16x32_bf16 v[0:3], v[4:7], v[20:23], v[0:3]
	ds_read_b128 v[4:7], v64 offset:40448
	ds_read_b128 v[102:105], v64 offset:40512
	s_waitcnt lgkmcnt(4)
	v_mfma_f32_16x16x32_bf16 v[8:11], v[12:15], v[20:23], v[8:11]
	s_nop 3
	v_cndmask_b32_e32 v0, v86, v0, vcc
	v_cmp_ne_u32_e32 vcc, 0, v106
	s_waitcnt lgkmcnt(3)
	v_mfma_f32_16x16x32_bf16 v[12:15], v[94:97], v[16:19], 0
	v_cndmask_b32_e32 v1, v86, v1, vcc
	v_cmp_ne_u32_e32 vcc, 0, v93
	v_and_b32_e32 v93, v70, v77
	s_waitcnt lgkmcnt(1)
	v_mfma_f32_16x16x32_bf16 v[94:97], v[4:7], v[16:19], 0
	v_cndmask_b32_e32 v2, v86, v2, vcc
	v_cmp_ne_u32_e32 vcc, 0, v93
	v_and_b32_e32 v4, v70, v78
	v_and_b32_e32 v5, v70, v79
	v_cndmask_b32_e32 v3, v86, v3, vcc
	v_cmp_ne_u32_e32 vcc, 0, v4
	v_mfma_f32_16x16x32_bf16 v[12:15], v[98:101], v[20:23], v[12:15]
	v_and_b32_e32 v6, v70, v80
	v_cndmask_b32_e32 v4, v86, v8, vcc
	v_cmp_ne_u32_e32 vcc, 0, v5
	v_and_b32_e32 v7, v70, v81
	v_and_b32_e32 v8, v71, v59
	v_cndmask_b32_e32 v5, v86, v9, vcc
	v_cmp_ne_u32_e32 vcc, 0, v6
	v_and_b32_e32 v9, v71, v75
	s_waitcnt lgkmcnt(0)
	ds_read_b64_tr_b16 v[140:141], v74 offset:32768
	ds_read_b64_tr_b16 v[144:145], v74 offset:32800
	ds_read_b64_tr_b16 v[148:149], v74 offset:32832
	ds_read_b64_tr_b16 v[152:153], v74 offset:32864
	ds_read_b64_tr_b16 v[142:143], v74 offset:35328
	ds_read_b64_tr_b16 v[146:147], v74 offset:35360
	ds_read_b64_tr_b16 v[150:151], v74 offset:35392
	ds_read_b64_tr_b16 v[154:155], v74 offset:35424
	ds_read_b64_tr_b16 v[156:157], v82 offset:32768
	ds_read_b64_tr_b16 v[160:161], v82 offset:32800
	ds_read_b64_tr_b16 v[164:165], v82 offset:32832
	ds_read_b64_tr_b16 v[168:169], v82 offset:32864
	ds_read_b64_tr_b16 v[158:159], v82 offset:35328
	ds_read_b64_tr_b16 v[162:163], v82 offset:35360
	ds_read_b64_tr_b16 v[166:167], v82 offset:35392
	ds_read_b64_tr_b16 v[170:171], v82 offset:35424
	v_mfma_f32_16x16x32_bf16 v[94:97], v[102:105], v[20:23], v[94:97]
	v_cndmask_b32_e32 v6, v86, v10, vcc
	v_cmp_ne_u32_e32 vcc, 0, v7
	v_and_b32_e32 v10, v71, v76
	s_nop 0
	v_cndmask_b32_e32 v7, v86, v11, vcc
	v_cmp_ne_u32_e32 vcc, 0, v8
	v_and_b32_e32 v11, v71, v77
	s_nop 0
	v_cndmask_b32_e32 v8, v86, v12, vcc
	v_cmp_ne_u32_e32 vcc, 0, v9
	v_and_b32_e32 v12, v71, v78
	s_nop 0
	v_cndmask_b32_e32 v9, v86, v13, vcc
	v_cmp_ne_u32_e32 vcc, 0, v10
	v_and_b32_e32 v13, v71, v79
	s_nop 0
	v_cndmask_b32_e32 v10, v86, v14, vcc
	v_cmp_ne_u32_e32 vcc, 0, v11
	v_and_b32_e32 v14, v71, v80
	v_cmp_ne_u32_e64 s[0:1], 0, v14
	v_cndmask_b32_e32 v11, v86, v15, vcc
	v_cmp_ne_u32_e32 vcc, 0, v12
	v_and_b32_e32 v15, v71, v81
	v_cndmask_b32_e64 v14, v86, v96, s[0:1]
	v_cndmask_b32_e32 v12, v86, v94, vcc
	v_cmp_ne_u32_e32 vcc, 0, v13
	s_nop 1
	v_cndmask_b32_e32 v13, v86, v95, vcc
	v_cmp_ne_u32_e32 vcc, 0, v15
	s_nop 1
	v_cndmask_b32_e32 v15, v86, v97, vcc
	s_cbranch_scc1 .LBB0_1675
	v_add_u32_e32 v70, s90, v72
	v_add_u32_e32 v71, 64, v70
	v_cmp_gt_u32_e32 vcc, s86, v71
	v_add_u32_e32 v71, 0x41, v70
	s_nop 0
	v_cndmask_b32_e32 v0, v86, v0, vcc
	v_cmp_gt_u32_e32 vcc, s86, v71
	v_add_u32_e32 v71, 0x42, v70
	s_nop 0
	v_cndmask_b32_e32 v1, v86, v1, vcc
	v_cmp_gt_u32_e32 vcc, s86, v71
	v_add_u32_e32 v71, 0x43, v70
	s_nop 0
	v_cndmask_b32_e32 v2, v86, v2, vcc
	v_cmp_gt_u32_e32 vcc, s86, v71
	v_add_u32_e32 v71, 0x50, v70
	v_cmp_gt_u32_e64 s[0:1], s86, v71
	v_add_u32_e32 v71, 0x51, v70
	v_cmp_gt_u32_e64 s[2:3], s86, v71
	v_add_u32_e32 v71, 0x52, v70
	v_cmp_gt_u32_e64 s[4:5], s86, v71
	v_add_u32_e32 v71, 0x53, v70
	v_cmp_gt_u32_e64 s[6:7], s86, v71
	v_add_u32_e32 v71, 0x60, v70
	v_cmp_gt_u32_e64 s[12:13], s86, v71
	v_add_u32_e32 v71, 0x61, v70
	v_cmp_gt_u32_e64 s[14:15], s86, v71
	v_add_u32_e32 v71, 0x62, v70
	v_cmp_gt_u32_e64 s[16:17], s86, v71
	v_add_u32_e32 v71, 0x63, v70
	v_cmp_gt_u32_e64 s[18:19], s86, v71
	v_add_u32_e32 v71, 0x70, v70
	v_cmp_gt_u32_e64 s[20:21], s86, v71
	v_add_u32_e32 v71, 0x71, v70
	v_cmp_gt_u32_e64 s[22:23], s86, v71
	v_add_u32_e32 v71, 0x72, v70
	v_add_u32_e32 v70, 0x73, v70
	v_cmp_gt_u32_e64 s[24:25], s86, v71
	v_cmp_gt_u32_e64 s[26:27], s86, v70
	s_or_b64 s[24:25], s[26:27], s[24:25]
	s_or_b64 s[22:23], s[24:25], s[22:23]
	s_or_b64 s[20:21], s[22:23], s[20:21]
	s_or_b64 s[18:19], s[20:21], s[18:19]
	s_or_b64 s[16:17], s[18:19], s[16:17]
	s_or_b64 s[14:15], s[16:17], s[14:15]
	s_or_b64 s[12:13], s[14:15], s[12:13]
	s_or_b64 s[6:7], s[12:13], s[6:7]
	s_or_b64 s[4:5], s[6:7], s[4:5]
	s_or_b64 s[2:3], s[4:5], s[2:3]
	s_or_b64 s[0:1], s[2:3], s[0:1]
	s_or_b64 vcc, s[0:1], vcc
	v_cndmask_b32_e64 v14, v86, v14, s[24:25]
	v_cndmask_b32_e64 v13, v86, v13, s[22:23]
	v_cndmask_b32_e64 v12, v86, v12, s[20:21]
	v_cndmask_b32_e64 v11, v86, v11, s[18:19]
	v_cndmask_b32_e64 v10, v86, v10, s[16:17]
	v_cndmask_b32_e64 v9, v86, v9, s[14:15]
	v_cndmask_b32_e64 v8, v86, v8, s[12:13]
	v_cndmask_b32_e64 v7, v86, v7, s[6:7]
	v_cndmask_b32_e64 v6, v86, v6, s[4:5]
	v_cndmask_b32_e64 v5, v86, v5, s[2:3]
	v_cndmask_b32_e64 v4, v86, v4, s[0:1]
	v_cndmask_b32_e32 v3, v86, v3, vcc
	v_cndmask_b32_e64 v15, v86, v15, s[26:27]
	s_branch .LBB0_1675
